# P6 and P8 epilogue vector loads de-serialized, permlane swaps for q/k-norm row reductions, on top of combo1+mod+norm
# speedup vs baseline: 1.0125x; 1.0013x over previous
;     __device__ __forceinline__ void operator()(const f32x4 (&acc)[2][2][4][2], const Unit& u, int wr, int wc, int fr, int fq) const {
;     ...
;             const int col0 = u.pn * BM + wc * 32 + 8 * fq; const int bo = (u.pm >= 32) ? ival : 0;
;             f32x4 gv[2][2], gm[2][2];
; #pragma unroll
;             for (int bj = 0; bj < 2; ++bj)
; #pragma unroll
;                 for (int n = 0; n < 2; ++n) { gv[bj][n] = *(const f32x4*)(gate + bo + col0 + bj * HALF + 4 * n);
;                     if (kind == 2) gm[bj][n] = *(const f32x4*)(ng + col0 + bj * HALF + 4 * n) * (*(const f32x4*)(scl + bo + col0 + bj * HALF + 4 * n) + 1.0f); }
; #pragma unroll
;             for (int ai = 0; ai < 2; ++ai)
; #pragma unroll
;                 for (int mp = 0; mp < 4 / MB; ++mp) {
;                     f32x4 bs[MB][2][2];
; #pragma unroll
;                     for (int mi = 0; mi < MB; ++mi) { const size_t off = (size_t)(row0 + ai * HALF + (MB * mp + mi) * 16) * 1024 + col0;
; #pragma unroll
;                         for (int bj = 0; bj < 2; ++bj)
; #pragma unroll
;                             for (int n = 0; n < 2; ++n) bs[mi][bj][n] = *(const f32x4*)(base + off + bj * HALF + 4 * n); }
; #pragma unroll
;                     for (int mi = 0; mi < MB; ++mi) { const int m = MB * mp + mi; const int row = row0 + ai * HALF + m * 16; const size_t off = (size_t)row * 1024 + col0;
;                         float ss = 0.f;
; #pragma unroll
;                         for (int bj = 0; bj < 2; ++bj) { f32x4 x1[2];
; #pragma unroll
;                             for (int n = 0; n < 2; ++n) { x1[n] = bs[mi][bj][n] + gv[bj][n] * acc[ai][bj][m][n];
;                                 *(f32x4*)(out + off + bj * HALF + 4 * n) = x1[n]; }
;                             if (kind == 2) { ss += (x1[0][0] * x1[0][0] + x1[0][1] * x1[0][1]) + (x1[0][2] * x1[0][2] + x1[0][3] * x1[0][3]) + (x1[1][0] * x1[1][0] + x1[1][1] * x1[1][1]) + (x1[1][2] * x1[1][2] + x1[1][3] * x1[1][3]);
;                                 const f32x4 a0 = x1[0] * gm[bj][0], a1 = x1[1] * gm[bj][1];
;                                 u32x4 w; w.x = cvt_pk_bf16(a0[0], a0[1]); w.y = cvt_pk_bf16(a0[2], a0[3]); w.z = cvt_pk_bf16(a1[0], a1[1]); w.w = cvt_pk_bf16(a1[2], a1[3]);
;                                 *(u32x4*)(A1 + off + bj * HALF) = w; } }
.LBB0_545:
	s_cmp_gt_i32 s56, 31
	v_lshl_or_b32 v196, s58, 8, v220
	s_cselect_b32 s16, 0x3000, 0
	s_add_u32 s14, s81, s16
	v_ashrrev_i32_e32 v197, 31, v196
	s_addc_u32 s15, s82, 0
	v_lshlrev_b64 v[160:161], 2, v[196:197]
	v_lshl_add_u64 v[152:153], s[14:15], 0, v[160:161]
	s_add_u32 s14, s83, s16
	s_addc_u32 s15, s84, 0
	v_lshl_add_u64 v[154:155], s[40:41], 0, v[160:161]
	v_lshl_add_u64 v[156:157], s[14:15], 0, v[160:161]
	global_load_dwordx4 v[88:91], v[152:153], off offset:16
	global_load_dwordx4 v[92:95], v[152:153], off
	global_load_dwordx4 v[72:75], v[154:155], off offset:16
	global_load_dwordx4 v[76:79], v[154:155], off
	global_load_dwordx4 v[144:147], v[156:157], off offset:16
	global_load_dwordx4 v[148:151], v[156:157], off
	global_load_dwordx4 v[224:227], v[152:153], off offset:528
	global_load_dwordx4 v[228:231], v[152:153], off offset:512
	global_load_dwordx4 v[232:235], v[154:155], off offset:528
	global_load_dwordx4 v[236:239], v[154:155], off offset:512
	global_load_dwordx4 v[240:243], v[156:157], off offset:528
	global_load_dwordx4 v[244:247], v[156:157], off offset:512
	v_lshl_add_u32 v200, s56, 8, v218
	v_ashrrev_i32_e32 v201, 31, v200
	v_lshl_add_u64 v[198:199], s[68:69], 0, v[160:161]
	v_or_b32_e32 v202, 16, v200
	v_ashrrev_i32_e32 v203, 31, v202
	v_lshlrev_b64 v[204:205], 10, v[200:201]
	v_lshl_add_u64 v[204:205], v[204:205], 0, v[196:197]
	v_lshl_add_u64 v[206:207], v[204:205], 2, s[8:9]
	v_lshl_add_u64 v[204:205], v[204:205], 1, s[12:13]
	v_cmp_lt_i32_e32 vcc, v211, v209
	s_waitcnt vmcnt(0)
	v_pk_add_f32 v[150:151], v[150:151], 1.0 op_sel_hi:[1,0]
	v_pk_add_f32 v[148:149], v[148:149], 1.0 op_sel_hi:[1,0]
	v_pk_mul_f32 v[190:191], v[78:79], v[150:151]
	v_pk_mul_f32 v[194:195], v[76:77], v[148:149]
	v_pk_add_f32 v[76:77], v[146:147], 1.0 op_sel_hi:[1,0]
	v_pk_add_f32 v[78:79], v[144:145], 1.0 op_sel_hi:[1,0]
	v_pk_mul_f32 v[188:189], v[74:75], v[76:77]
	v_pk_mul_f32 v[192:193], v[72:73], v[78:79]
	v_mov_b64_e32 v[72:73], v[224:225]
	v_mov_b64_e32 v[74:75], v[226:227]
	v_mov_b64_e32 v[76:77], v[228:229]
	v_mov_b64_e32 v[78:79], v[230:231]
	v_mov_b64_e32 v[144:145], v[232:233]
	v_mov_b64_e32 v[146:147], v[234:235]
	v_mov_b64_e32 v[148:149], v[236:237]
	v_mov_b64_e32 v[150:151], v[238:239]
	s_nop 0
	v_mov_b64_e32 v[152:153], v[240:241]
	v_mov_b64_e32 v[154:155], v[242:243]
	s_nop 0
	v_mov_b64_e32 v[156:157], v[244:245]
	v_mov_b64_e32 v[158:159], v[246:247]
	s_waitcnt vmcnt(0)
	v_pk_add_f32 v[158:159], v[158:159], 1.0 op_sel_hi:[1,0]
	s_nop 0
	v_pk_mul_f32 v[186:187], v[150:151], v[158:159]
	v_pk_add_f32 v[150:151], v[152:153], 1.0 op_sel_hi:[1,0]
	v_pk_add_f32 v[156:157], v[156:157], 1.0 op_sel_hi:[1,0]
	v_pk_mul_f32 v[184:185], v[144:145], v[150:151]
	v_lshlrev_b64 v[144:145], 12, v[200:201]
	v_lshl_add_u64 v[144:145], v[198:199], 0, v[144:145]
	global_load_dwordx4 v[224:227], v[144:145], off offset:16
	global_load_dwordx4 v[228:231], v[144:145], off
	global_load_dwordx4 v[160:163], v[144:145], off offset:528
	global_load_dwordx4 v[232:235], v[144:145], off offset:512
	v_pk_mul_f32 v[180:181], v[148:149], v[156:157]
	v_pk_add_f32 v[148:149], v[154:155], 1.0 op_sel_hi:[1,0]
	v_lshlrev_b64 v[144:145], 12, v[202:203]
	v_pk_mul_f32 v[182:183], v[146:147], v[148:149]
	v_lshl_add_u64 v[148:149], v[198:199], 0, v[144:145]
	global_load_dwordx4 v[152:155], v[148:149], off offset:16
	global_load_dwordx4 v[156:159], v[148:149], off
	global_load_dwordx4 v[144:147], v[148:149], off offset:528
	s_nop 0
	global_load_dwordx4 v[148:151], v[148:149], off offset:512
	s_waitcnt vmcnt(7)
	v_pk_fma_f32 v[136:137], v[136:137], v[88:89], v[224:225]
	s_waitcnt vmcnt(6)
	v_pk_fma_f32 v[142:143], v[142:143], v[94:95], v[230:231]
	v_pk_fma_f32 v[140:141], v[140:141], v[92:93], v[228:229]
	v_mul_f32_e32 v225, v143, v143
	v_mul_f32_e32 v224, v141, v141
	v_fmac_f32_e32 v224, v140, v140
	v_fmac_f32_e32 v225, v142, v142
	v_add_f32_e32 v224, v224, v225
	v_mul_f32_e32 v225, v137, v137
	v_pk_fma_f32 v[138:139], v[138:139], v[90:91], v[226:227]
	v_fmac_f32_e32 v225, v136, v136
	v_add_f32_e32 v224, v224, v225
	v_mul_f32_e32 v225, v139, v139
	v_fmac_f32_e32 v225, v138, v138
	global_store_dwordx4 v[206:207], v[140:143], off
	global_store_dwordx4 v[206:207], v[136:139], off offset:16
	v_add_f32_e32 v226, v225, v224
	v_pk_mul_f32 v[142:143], v[190:191], v[142:143]
	v_pk_mul_f32 v[140:141], v[194:195], v[140:141]
	v_pk_mul_f32 v[224:225], v[188:189], v[138:139]
	v_pk_mul_f32 v[138:139], v[192:193], v[136:137]
	v_cvt_pk_bf16_f32 v136, v140, v141
	v_cvt_pk_bf16_f32 v137, v142, v143
	s_waitcnt vmcnt(6)
	v_pk_fma_f32 v[134:135], v[134:135], v[78:79], v[234:235]
	v_pk_fma_f32 v[132:133], v[132:133], v[76:77], v[232:233]
	v_cvt_pk_bf16_f32 v138, v138, v139
	v_cvt_pk_bf16_f32 v139, v224, v225
	global_store_dwordx4 v[204:205], v[136:139], off
	v_pk_fma_f32 v[128:129], v[128:129], v[72:73], v[160:161]
	v_pk_fma_f32 v[130:131], v[130:131], v[74:75], v[162:163]
	v_mul_f32_e32 v136, v133, v133
	v_mul_f32_e32 v137, v135, v135
	v_fmac_f32_e32 v136, v132, v132
	v_fmac_f32_e32 v137, v134, v134
	v_add_f32_e32 v136, v136, v137
	v_mul_f32_e32 v137, v129, v129
	v_fmac_f32_e32 v137, v128, v128
	v_add_f32_e32 v136, v136, v137
	v_mul_f32_e32 v137, v131, v131
	v_fmac_f32_e32 v137, v130, v130
	v_add_f32_e32 v136, v137, v136
	global_store_dwordx4 v[206:207], v[132:135], off offset:512
	global_store_dwordx4 v[206:207], v[128:131], off offset:528
	v_add_f32_e32 v138, v226, v136
	v_pk_mul_f32 v[132:133], v[180:181], v[132:133]
	v_pk_mul_f32 v[136:137], v[182:183], v[130:131]
	v_pk_mul_f32 v[130:131], v[184:185], v[128:129]
	v_cvt_pk_bf16_f32 v128, v132, v133
	v_pk_mul_f32 v[134:135], v[186:187], v[134:135]
	s_nop 0
	v_cvt_pk_bf16_f32 v129, v134, v135
	v_cvt_pk_bf16_f32 v130, v130, v131
	v_cvt_pk_bf16_f32 v131, v136, v137
	global_store_dwordx4 v[204:205], v[128:131], off offset:256
	s_nop 1
	v_cndmask_b32_e32 v128, v208, v211, vcc
	v_lshlrev_b32_e32 v132, 2, v128
	ds_bpermute_b32 v128, v132, v138
	v_cmp_lt_i32_e32 vcc, v210, v209
	s_waitcnt lgkmcnt(0)
	v_add_f32_e32 v128, v138, v128
	v_cndmask_b32_e32 v129, v208, v210, vcc
	v_lshlrev_b32_e32 v133, 2, v129
	ds_bpermute_b32 v129, v133, v128
	s_and_saveexec_b64 s[18:19], s[36:37]
	s_cbranch_execz .LBB0_547
	v_lshl_add_u64 v[130:131], v[200:201], 2, s[42:43]
	s_waitcnt lgkmcnt(0)
	v_add_f32_e32 v128, v128, v129
	global_atomic_add_f32 v[130:131], v128, off

;     __device__ __forceinline__ void operator()(const f32x4 (&acc)[2][2][4][2], const Unit& u, int wr, int wc, int fr, int fq) const {
;     ...
;             const int type = u.pn >> 2, head = 4 * (u.pn & 3) + wc;
;             bf16_t* base = QKVG + (size_t)type * ((size_t)16384 * 1024) + head * 64 + 8 * fq;
;             const float* bp = biasp + (u.pm >= 32 ? 4352 : 0) + u.pn * BM + wc * 32 + 8 * fq;
;             f32x4 gg[2][2], bb[2][2];
; #pragma unroll
;             for (int bj = 0; bj < 2; ++bj)
; #pragma unroll
;                 for (int n = 0; n < 2; ++n) { f32x4 g1 = (f32x4){1.f, 1.f, 1.f, 1.f};
;                     if (type == 0) g1 = *(const f32x4*)(gq + 32 * bj + 8 * fq + 4 * n) * c2; else if (type == 1) g1 = *(const f32x4*)(gk + 32 * bj + 8 * fq + 4 * n);
;                     gg[bj][n] = g1; bb[bj][n] = *(const f32x4*)(bp + bj * HALF + 4 * n); }
.LBB0_640:
	s_mov_b32 s98, 0
	s_ashr_i32 s68, s60, 2
	s_cmp_gt_u32 s60, 3
	s_cselect_b64 s[18:19], -1, 0
	s_cmp_eq_u32 s68, 1
	s_cselect_b64 s[14:15], -1, 0
	v_cndmask_b32_e64 v72, 0, 1, s[14:15]
	s_mov_b64 s[40:41], -1
	s_and_b64 vcc, exec, s[18:19]
	v_cmp_ne_u32_e64 s[38:39], 1, v72
	s_cbranch_vccz .LBB0_644
	v_mov_b32_e32 v75, 1.0
	s_and_b64 vcc, exec, s[38:39]
	v_mov_b32_e32 v74, 1.0
	v_mov_b32_e32 v73, 1.0
	v_mov_b32_e32 v72, 1.0
	s_cbranch_vccnz .LBB0_643
	global_load_dwordx4 v[72:75], v[172:173], off

;     __device__ __forceinline__ void operator()(const f32x4 (&acc)[2][2][4][2], const Unit& u, int wr, int wc, int fr, int fq) const {
;     ...
;                     if (type == 0) g1 = *(const f32x4*)(gq + 32 * bj + 8 * fq + 4 * n) * c2; else if (type == 1) g1 = *(const f32x4*)(gk + 32 * bj + 8 * fq + 4 * n);
;                     gg[bj][n] = g1; bb[bj][n] = *(const f32x4*)(bp + bj * HALF + 4 * n); }
.LBB0_644:
	s_andn2_b64 vcc, exec, s[40:41]
	s_cbranch_vccnz .LBB0_646
	global_load_dwordx4 v[72:75], v[174:175], off
	s_mov_b32 s98, 1

;     __device__ __forceinline__ void operator()(const f32x4 (&acc)[2][2][4][2], const Unit& u, int wr, int wc, int fr, int fq) const {
;     ...
;             for (int bj = 0; bj < 2; ++bj)
; #pragma unroll
;                 for (int n = 0; n < 2; ++n) { f32x4 g1 = (f32x4){1.f, 1.f, 1.f, 1.f};
;                     if (type == 0) g1 = *(const f32x4*)(gq + 32 * bj + 8 * fq + 4 * n) * c2; else if (type == 1) g1 = *(const f32x4*)(gk + 32 * bj + 8 * fq + 4 * n);
;                     gg[bj][n] = g1; bb[bj][n] = *(const f32x4*)(bp + bj * HALF + 4 * n); }
.LBB0_650:
	s_andn2_b64 vcc, exec, s[18:19]
	s_cbranch_vccnz .LBB0_652
	global_load_dwordx4 v[84:87], v[174:175], off offset:16
.LBB0_652:
	v_lshl_add_u64 v[140:141], s[72:73], 0, v[168:169]
	global_load_dwordx4 v[116:119], v[140:141], off offset:16
	s_and_b64 vcc, exec, s[40:41]
	s_mov_b64 s[18:19], -1
	s_cbranch_vccnz .LBB0_656
	v_mov_b32_e32 v99, 1.0
	s_and_b64 vcc, exec, s[38:39]
	v_mov_b32_e32 v98, 1.0
	v_mov_b32_e32 v97, 1.0
	v_mov_b32_e32 v96, 1.0
	s_cbranch_vccnz .LBB0_655
	global_load_dwordx4 v[96:99], v[172:173], off offset:128

;     __device__ __forceinline__ void operator()(const f32x4 (&acc)[2][2][4][2], const Unit& u, int wr, int wc, int fr, int fq) const {
;     ...
;             for (int bj = 0; bj < 2; ++bj)
; #pragma unroll
;                 for (int n = 0; n < 2; ++n) { f32x4 g1 = (f32x4){1.f, 1.f, 1.f, 1.f};
;                     if (type == 0) g1 = *(const f32x4*)(gq + 32 * bj + 8 * fq + 4 * n) * c2; else if (type == 1) g1 = *(const f32x4*)(gk + 32 * bj + 8 * fq + 4 * n);
;                     gg[bj][n] = g1; bb[bj][n] = *(const f32x4*)(bp + bj * HALF + 4 * n); }
.LBB0_657:
	global_load_dwordx4 v[96:99], v[174:175], off offset:128
.LBB0_658:
	global_load_dwordx4 v[128:131], v[140:141], off offset:512
	s_and_b64 vcc, exec, s[40:41]
	s_mov_b64 s[18:19], -1
	s_cbranch_vccnz .LBB0_662
	v_mov_b32_e32 v115, 1.0
	s_and_b64 vcc, exec, s[38:39]
	v_mov_b32_e32 v114, 1.0
	v_mov_b32_e32 v113, 1.0
	v_mov_b32_e32 v112, 1.0
	s_cbranch_vccnz .LBB0_661
	global_load_dwordx4 v[112:115], v[172:173], off offset:144

; __device__ __forceinline__ unsigned cvt_pk_bf16(float lo, float hi) { unsigned r; asm volatile("v_cvt_pk_bf16_f32 %0, %1, %2" : "=v"(r) : "v"(lo), "v"(hi)); return r; }
; __device__ __forceinline__ void st16_wt(void* p, u32x4 v) { asm volatile("global_store_dwordx4 %0, %1, off sc1\n\ts_nop 1" :: "v"(p), "v"(v) : "memory"); }
;     __device__ __forceinline__ void operator()(const f32x4 (&acc)[2][2][4][2], const Unit& u, int wr, int wc, int fr, int fq) const {
;     ...
;                     if (type == 0) g1 = *(const f32x4*)(gq + 32 * bj + 8 * fq + 4 * n) * c2; else if (type == 1) g1 = *(const f32x4*)(gk + 32 * bj + 8 * fq + 4 * n);
;                     gg[bj][n] = g1; bb[bj][n] = *(const f32x4*)(bp + bj * HALF + 4 * n); }
;     ...
;                 for (int m = 0; m < 4; ++m) rr8[ai][m] = rowss[row0 + ai * HALF + m * 16];
; #pragma unroll
;             for (int ai = 0; ai < 2; ++ai)
; #pragma unroll
;                 for (int m = 0; m < 4; ++m) {
;                     const int row = row0 + ai * HALF + m * 16;
;                     const float rrow = __builtin_amdgcn_rsqf(rr8[ai][m] * (1.0f / 1024.0f) + 1e-6f);
;                     f32x4 v[2][2];
; #pragma unroll
;                     for (int bj = 0; bj < 2; ++bj)
; #pragma unroll
;                         for (int n = 0; n < 2; ++n) v[bj][n] = acc[ai][bj][m][n] * rrow + bb[bj][n];
;                     float rs = 1.f;
;                     if (type < 2) { float ss = 0.f;
; #pragma unroll
;                         for (int bj = 0; bj < 2; ++bj)
; #pragma unroll
;                             for (int n = 0; n < 2; ++n) { const f32x4 x = v[bj][n]; ss += (x[0] * x[0] + x[1] * x[1]) + (x[2] * x[2] + x[3] * x[3]); }
;                         ss += __shfl_xor(ss, 16); ss += __shfl_xor(ss, 32);
;                         rs = __builtin_amdgcn_rsqf(ss * (1.0f / 64.0f) + 1e-6f); }
;                     bf16_t* rowp = base + (size_t)row * 1024;
; #pragma unroll
;                     for (int bj = 0; bj < 2; ++bj) { const f32x4 v0 = v[bj][0] * rs * gg[bj][0], v1 = v[bj][1] * rs * gg[bj][1];
;                         u32x4 w; w.x = cvt_pk_bf16(v0[0], v0[1]); w.y = cvt_pk_bf16(v0[2], v0[3]); w.z = cvt_pk_bf16(v1[0], v1[1]); w.w = cvt_pk_bf16(v1[2], v1[3]);
;                         st16_wt(rowp + 32 * bj, w); } }
.LBB0_664:
	v_lshl_add_u32 v184, s66, 8, v171
	v_or_b32_e32 v190, 16, v184
	v_ashrrev_i32_e32 v185, 31, v184
	v_ashrrev_i32_e32 v191, 31, v190
	v_or_b32_e32 v188, 32, v184
	v_lshl_add_u64 v[192:193], v[184:185], 2, s[42:43]
	v_lshl_add_u64 v[186:187], v[190:191], 2, s[42:43]
	v_ashrrev_i32_e32 v189, 31, v188
	global_load_dwordx4 v[140:143], v[140:141], off offset:528
	s_cmp_lt_i32 s68, 2
	global_load_dword v196, v[192:193], off
	global_load_dword v218, v[186:187], off
	v_lshl_add_u64 v[186:187], v[188:189], 2, s[42:43]
	global_load_dword v207, v[186:187], off
	v_or_b32_e32 v186, 48, v184
	v_ashrrev_i32_e32 v187, 31, v186
	v_lshl_add_u64 v[194:195], v[186:187], 2, s[42:43]
	global_load_dword v206, v[194:195], off
	global_load_dword v205, v[192:193], off offset:512
	global_load_dword v204, v[192:193], off offset:576
	global_load_dword v203, v[192:193], off offset:640
	global_load_dword v202, v[192:193], off offset:704
	s_cselect_b64 s[40:41], -1, 0
	s_cmp_gt_i32 s68, 1
	s_waitcnt vmcnt(0)
	s_cselect_b32 s99, 1, 0
	s_cmp_eq_u32 s98, 0
	s_cbranch_scc1 .Lp8e_skip
	v_pk_mul_f32 v[74:75], v[74:75], s[50:51] op_sel_hi:[1,0]
	v_pk_mul_f32 v[72:73], v[72:73], s[50:51] op_sel_hi:[1,0]
	v_pk_mul_f32 v[86:87], v[86:87], s[50:51] op_sel_hi:[1,0]
	v_pk_mul_f32 v[84:85], v[84:85], s[50:51] op_sel_hi:[1,0]
	v_pk_mul_f32 v[98:99], v[98:99], s[50:51] op_sel_hi:[1,0]
	v_pk_mul_f32 v[96:97], v[96:97], s[50:51] op_sel_hi:[1,0]
	v_pk_mul_f32 v[114:115], v[114:115], s[50:51] op_sel_hi:[1,0]
	v_pk_mul_f32 v[112:113], v[112:113], s[50:51] op_sel_hi:[1,0]
.Lp8e_skip:
	s_cmp_lg_u32 s99, 0
	v_fmamk_f32 v192, v196, 0x3a800000, v201
	v_rsq_f32_e32 v196, v192
	s_nop 0
	v_pk_fma_f32 v[192:193], v[158:159], v[196:197], v[102:103] op_sel_hi:[1,0,1]
	v_pk_fma_f32 v[194:195], v[156:157], v[196:197], v[100:101] op_sel_hi:[1,0,1]
	v_pk_fma_f32 v[156:157], v[154:155], v[196:197], v[118:119] op_sel_hi:[1,0,1]
	v_pk_fma_f32 v[158:159], v[152:153], v[196:197], v[116:117] op_sel_hi:[1,0,1]
	v_pk_fma_f32 v[152:153], v[150:151], v[196:197], v[130:131] op_sel_hi:[1,0,1]
	v_pk_fma_f32 v[154:155], v[148:149], v[196:197], v[128:129] op_sel_hi:[1,0,1]
	v_pk_fma_f32 v[148:149], v[146:147], v[196:197], v[142:143] op_sel_hi:[1,0,1]
	v_pk_fma_f32 v[150:151], v[144:145], v[196:197], v[140:141] op_sel_hi:[1,0,1]
	v_mov_b32_e32 v146, 1.0
	v_mov_b32_e32 v196, 1.0
	s_cbranch_scc1 .LBB0_666
	v_pk_mul_f32 v[144:145], v[192:193], v[192:193]
	v_pk_mul_f32 v[220:221], v[194:195], v[194:195]
	v_cmp_lt_i32_e32 vcc, v211, v209
	v_pk_mov_b32 v[222:223], v[220:221], v[144:145] op_sel:[1,0]
	v_mov_b32_e32 v221, v145
	v_pk_add_f32 v[144:145], v[222:223], v[220:221]
	v_pk_mul_f32 v[220:221], v[156:157], v[156:157]
	v_pk_add_f32 v[144:145], v[144:145], v[144:145] op_sel_hi:[0,1]
	v_pk_mul_f32 v[222:223], v[158:159], v[158:159]
	v_mul_f32_e32 v144, v154, v154
	v_pk_mov_b32 v[224:225], v[222:223], v[220:221] op_sel:[1,0]
	v_mov_b32_e32 v223, v221
	v_pk_add_f32 v[220:221], v[224:225], v[222:223]
	v_pk_fma_f32 v[222:223], v[154:155], v[154:155], v[144:145] op_sel_hi:[1,1,0]
	v_mul_f32_e32 v144, v152, v152
	v_pk_add_f32 v[220:221], v[220:221], v[220:221] op_sel_hi:[0,1]
	v_pk_fma_f32 v[224:225], v[152:153], v[152:153], v[144:145] op_sel_hi:[1,1,0]
	v_mul_f32_e32 v222, v150, v150
	v_mul_f32_e32 v224, v151, v151
	v_mul_f32_e32 v144, v148, v148
	v_mul_f32_e32 v220, v149, v149
	v_pk_add_f32 v[222:223], v[222:223], v[224:225]
	v_pk_add_f32 v[144:145], v[144:145], v[220:221]
	s_nop 0
	v_pk_add_f32 v[144:145], v[222:223], v[144:145]
	s_nop 0
	v_add_f32_e32 v144, v144, v145
	v_mov_b32_e32 v145, v144
	s_nop 1
	v_permlane16_swap_b32_e32 v145, v144
	v_cmp_lt_i32_e32 vcc, v210, v209
	s_waitcnt lgkmcnt(0)
	v_add_f32_e32 v144, v144, v145
	v_mov_b32_e32 v145, v144
	s_nop 1
	v_permlane32_swap_b32_e32 v145, v144
	s_nop 1
	v_add_f32_e32 v144, v144, v145
	v_fmamk_f32 v144, v144, 0x3c800000, v201
	v_rsq_f32_e32 v196, v144
.LBB0_666:
	s_lshl_b32 s14, s60, 2
	s_and_b32 s14, s14, 12
	s_ashr_i32 s69, s68, 31
	s_or_b32 s16, s14, s77
	s_lshl_b64 s[14:15], s[68:69], 25
	s_add_u32 s14, s20, s14
	s_addc_u32 s15, s21, s15
	s_lshl_b32 s16, s16, 7
	s_add_u32 s14, s14, s16
	s_addc_u32 s15, s15, 0
	v_lshlrev_b32_e32 v144, 1, v170
	v_mov_b32_e32 v145, v169
	v_pk_mul_f32 v[192:193], v[192:193], v[196:197] op_sel_hi:[1,0]
	v_pk_mul_f32 v[194:195], v[194:195], v[196:197] op_sel_hi:[1,0]
	v_pk_mul_f32 v[156:157], v[156:157], v[196:197] op_sel_hi:[1,0]
	v_pk_mul_f32 v[158:159], v[158:159], v[196:197] op_sel_hi:[1,0]
	v_pk_mul_f32 v[152:153], v[152:153], v[196:197] op_sel_hi:[1,0]
	v_lshl_add_u64 v[144:145], s[14:15], 0, v[144:145]
	v_lshlrev_b64 v[220:221], 11, v[184:185]
	v_pk_mul_f32 v[192:193], v[74:75], v[192:193]
	v_pk_mul_f32 v[194:195], v[72:73], v[194:195]
	v_pk_mul_f32 v[222:223], v[86:87], v[156:157]
	v_pk_mul_f32 v[158:159], v[84:85], v[158:159]
	v_cvt_pk_bf16_f32 v156, v194, v195
	v_cvt_pk_bf16_f32 v157, v192, v193
	v_pk_mul_f32 v[154:155], v[154:155], v[196:197] op_sel_hi:[1,0]
	v_pk_mul_f32 v[152:153], v[98:99], v[152:153]
	v_pk_mul_f32 v[148:149], v[148:149], v[196:197] op_sel_hi:[1,0]
	v_fmamk_f32 v147, v218, 0x3a800000, v201
	v_lshl_add_u64 v[220:221], v[144:145], 0, v[220:221]
	v_cvt_pk_bf16_f32 v158, v158, v159
	v_cvt_pk_bf16_f32 v159, v222, v223
	v_pk_mul_f32 v[154:155], v[96:97], v[154:155]
	global_store_dwordx4 v[220:221], v[156:159], off sc1
	s_nop 1
	v_pk_mul_f32 v[150:151], v[150:151], v[196:197] op_sel_hi:[1,0]
	v_pk_mul_f32 v[156:157], v[114:115], v[148:149]
	v_cvt_pk_bf16_f32 v148, v154, v155
	v_cvt_pk_bf16_f32 v149, v152, v153
	v_rsq_f32_e32 v152, v147
	v_pk_mul_f32 v[150:151], v[112:113], v[150:151]
	v_lshl_add_u64 v[154:155], v[220:221], 0, 64
	v_cvt_pk_bf16_f32 v150, v150, v151
	v_cvt_pk_bf16_f32 v151, v156, v157
	v_cndmask_b32_e64 v147, 0, 1, s[40:41]
	global_store_dwordx4 v[154:155], v[148:151], off sc1
	s_nop 1
	v_pk_fma_f32 v[138:139], v[138:139], v[152:153], v[102:103] op_sel_hi:[1,0,1]
	v_pk_fma_f32 v[136:137], v[136:137], v[152:153], v[100:101] op_sel_hi:[1,0,1]
	v_pk_fma_f32 v[134:135], v[134:135], v[152:153], v[118:119] op_sel_hi:[1,0,1]
	v_pk_fma_f32 v[132:133], v[132:133], v[152:153], v[116:117] op_sel_hi:[1,0,1]
	v_pk_fma_f32 v[126:127], v[126:127], v[152:153], v[130:131] op_sel_hi:[1,0,1]
	v_pk_fma_f32 v[124:125], v[124:125], v[152:153], v[128:129] op_sel_hi:[1,0,1]
	v_pk_fma_f32 v[122:123], v[122:123], v[152:153], v[142:143] op_sel_hi:[1,0,1]
	v_cmp_ne_u32_e64 s[38:39], 1, v147
	s_andn2_b64 vcc, exec, s[40:41]
	v_pk_fma_f32 v[120:121], v[120:121], v[152:153], v[140:141] op_sel_hi:[1,0,1]
	s_cbranch_vccnz .LBB0_668
; __device__ __forceinline__ unsigned cvt_pk_bf16(float lo, float hi) { unsigned r; asm volatile("v_cvt_pk_bf16_f32 %0, %1, %2" : "=v"(r) : "v"(lo), "v"(hi)); return r; }
; __device__ __forceinline__ void st16_wt(void* p, u32x4 v) { asm volatile("global_store_dwordx4 %0, %1, off sc1\n\ts_nop 1" :: "v"(p), "v"(v) : "memory"); }
;     __device__ __forceinline__ void operator()(const f32x4 (&acc)[2][2][4][2], const Unit& u, int wr, int wc, int fr, int fq) const {
;     ...
;                 for (int m = 0; m < 4; ++m) {
;                     const int row = row0 + ai * HALF + m * 16;
;                     const float rrow = __builtin_amdgcn_rsqf(rr8[ai][m] * (1.0f / 1024.0f) + 1e-6f);
;                     f32x4 v[2][2];
; #pragma unroll
;                     for (int bj = 0; bj < 2; ++bj)
; #pragma unroll
;                         for (int n = 0; n < 2; ++n) v[bj][n] = acc[ai][bj][m][n] * rrow + bb[bj][n];
;                     float rs = 1.f;
;                     if (type < 2) { float ss = 0.f;
; #pragma unroll
;                         for (int bj = 0; bj < 2; ++bj)
; #pragma unroll
;                             for (int n = 0; n < 2; ++n) { const f32x4 x = v[bj][n]; ss += (x[0] * x[0] + x[1] * x[1]) + (x[2] * x[2] + x[3] * x[3]); }
;                         ss += __shfl_xor(ss, 16); ss += __shfl_xor(ss, 32);
;                         rs = __builtin_amdgcn_rsqf(ss * (1.0f / 64.0f) + 1e-6f); }
;                     bf16_t* rowp = base + (size_t)row * 1024;
; #pragma unroll
;                     for (int bj = 0; bj < 2; ++bj) { const f32x4 v0 = v[bj][0] * rs * gg[bj][0], v1 = v[bj][1] * rs * gg[bj][1];
;                         u32x4 w; w.x = cvt_pk_bf16(v0[0], v0[1]); w.y = cvt_pk_bf16(v0[2], v0[3]); w.z = cvt_pk_bf16(v1[0], v1[1]); w.w = cvt_pk_bf16(v1[2], v1[3]);
;                         st16_wt(rowp + 32 * bj, w); } }
	v_pk_mul_f32 v[146:147], v[138:139], v[138:139]
	v_pk_mul_f32 v[148:149], v[136:137], v[136:137]
	v_cmp_lt_i32_e32 vcc, v211, v209
	v_pk_mov_b32 v[150:151], v[148:149], v[146:147] op_sel:[1,0]
	v_mov_b32_e32 v149, v147
	v_pk_add_f32 v[146:147], v[150:151], v[148:149]
	v_pk_mul_f32 v[148:149], v[134:135], v[134:135]
	v_pk_add_f32 v[146:147], v[146:147], v[146:147] op_sel_hi:[0,1]
	v_pk_mul_f32 v[150:151], v[132:133], v[132:133]
	v_mul_f32_e32 v146, v124, v124
	v_pk_mov_b32 v[152:153], v[150:151], v[148:149] op_sel:[1,0]
	v_mov_b32_e32 v151, v149
	v_pk_add_f32 v[148:149], v[152:153], v[150:151]
	v_pk_fma_f32 v[150:151], v[124:125], v[124:125], v[146:147] op_sel_hi:[1,1,0]
	v_mul_f32_e32 v146, v126, v126
	v_pk_add_f32 v[148:149], v[148:149], v[148:149] op_sel_hi:[0,1]
	v_pk_fma_f32 v[152:153], v[126:127], v[126:127], v[146:147] op_sel_hi:[1,1,0]
	v_mul_f32_e32 v150, v120, v120
	v_mul_f32_e32 v152, v121, v121
	v_mul_f32_e32 v146, v122, v122
	v_mul_f32_e32 v148, v123, v123
	v_pk_add_f32 v[150:151], v[150:151], v[152:153]
	v_pk_add_f32 v[146:147], v[146:147], v[148:149]
	s_nop 0
	v_pk_add_f32 v[146:147], v[150:151], v[146:147]
	s_nop 0
	v_add_f32_e32 v146, v146, v147
	v_mov_b32_e32 v147, v146
	s_nop 1
	v_permlane16_swap_b32_e32 v147, v146
	v_cmp_lt_i32_e32 vcc, v210, v209
	s_waitcnt lgkmcnt(0)
	v_add_f32_e32 v146, v146, v147
	v_mov_b32_e32 v147, v146
	s_nop 1
	v_permlane32_swap_b32_e32 v147, v146
	s_nop 1
	v_add_f32_e32 v146, v146, v147
	v_fmamk_f32 v146, v146, 0x3c800000, v201
	v_rsq_f32_e32 v146, v146
.LBB0_668:
	s_nop 0
	v_pk_mul_f32 v[138:139], v[138:139], v[146:147] op_sel_hi:[1,0]
	v_pk_mul_f32 v[136:137], v[136:137], v[146:147] op_sel_hi:[1,0]
	v_pk_mul_f32 v[134:135], v[134:135], v[146:147] op_sel_hi:[1,0]
	v_pk_mul_f32 v[132:133], v[132:133], v[146:147] op_sel_hi:[1,0]
	v_lshlrev_b64 v[148:149], 11, v[190:191]
	v_pk_mul_f32 v[138:139], v[74:75], v[138:139]
	v_pk_mul_f32 v[136:137], v[72:73], v[136:137]
	v_pk_mul_f32 v[150:151], v[86:87], v[134:135]
	v_pk_mul_f32 v[134:135], v[84:85], v[132:133]
	v_cvt_pk_bf16_f32 v132, v136, v137
	v_cvt_pk_bf16_f32 v133, v138, v139
	v_pk_mul_f32 v[122:123], v[122:123], v[146:147] op_sel_hi:[1,0]
	v_pk_mul_f32 v[120:121], v[120:121], v[146:147] op_sel_hi:[1,0]
	v_lshl_add_u64 v[148:149], v[144:145], 0, v[148:149]
	v_cvt_pk_bf16_f32 v134, v134, v135
	v_cvt_pk_bf16_f32 v135, v150, v151
	v_pk_mul_f32 v[126:127], v[126:127], v[146:147] op_sel_hi:[1,0]
	global_store_dwordx4 v[148:149], v[132:135], off sc1
	s_nop 1
	v_pk_mul_f32 v[124:125], v[124:125], v[146:147] op_sel_hi:[1,0]
	v_pk_mul_f32 v[132:133], v[114:115], v[122:123]
	v_pk_mul_f32 v[122:123], v[112:113], v[120:121]
	v_pk_mul_f32 v[126:127], v[98:99], v[126:127]
	v_pk_mul_f32 v[124:125], v[96:97], v[124:125]
	s_and_b64 vcc, exec, s[38:39]
	v_cvt_pk_bf16_f32 v120, v124, v125
	v_cvt_pk_bf16_f32 v121, v126, v127
	v_cvt_pk_bf16_f32 v122, v122, v123
	v_fmamk_f32 v123, v207, 0x3a800000, v201
	v_rsq_f32_e32 v124, v123
	v_cvt_pk_bf16_f32 v123, v132, v133
	v_lshl_add_u64 v[126:127], v[148:149], 0, 64
	global_store_dwordx4 v[126:127], v[120:123], off sc1
	s_nop 1
	v_pk_fma_f32 v[110:111], v[110:111], v[124:125], v[102:103] op_sel_hi:[1,0,1]
	v_pk_fma_f32 v[120:121], v[108:109], v[124:125], v[100:101] op_sel_hi:[1,0,1]
	v_pk_fma_f32 v[106:107], v[106:107], v[124:125], v[118:119] op_sel_hi:[1,0,1]
	v_pk_fma_f32 v[108:109], v[104:105], v[124:125], v[116:117] op_sel_hi:[1,0,1]
	v_pk_fma_f32 v[94:95], v[94:95], v[124:125], v[130:131] op_sel_hi:[1,0,1]
	v_pk_fma_f32 v[104:105], v[92:93], v[124:125], v[128:129] op_sel_hi:[1,0,1]
	v_pk_fma_f32 v[90:91], v[90:91], v[124:125], v[142:143] op_sel_hi:[1,0,1]
	v_pk_fma_f32 v[92:93], v[88:89], v[124:125], v[140:141] op_sel_hi:[1,0,1]
	v_mov_b32_e32 v88, 1.0
	v_mov_b32_e32 v122, 1.0
	s_cbranch_vccnz .LBB0_670
	v_pk_mul_f32 v[122:123], v[110:111], v[110:111]
	v_pk_mul_f32 v[124:125], v[120:121], v[120:121]
	v_cmp_lt_i32_e32 vcc, v211, v209
	v_pk_mov_b32 v[126:127], v[124:125], v[122:123] op_sel:[1,0]
	v_mov_b32_e32 v125, v123
	v_pk_add_f32 v[122:123], v[126:127], v[124:125]
	v_pk_mul_f32 v[124:125], v[106:107], v[106:107]
	v_pk_add_f32 v[122:123], v[122:123], v[122:123] op_sel_hi:[0,1]
	v_pk_mul_f32 v[126:127], v[108:109], v[108:109]
	v_mul_f32_e32 v122, v104, v104
	v_pk_mov_b32 v[132:133], v[126:127], v[124:125] op_sel:[1,0]
	v_mov_b32_e32 v127, v125
	v_pk_add_f32 v[124:125], v[132:133], v[126:127]
	v_pk_fma_f32 v[126:127], v[104:105], v[104:105], v[122:123] op_sel_hi:[1,1,0]
	v_mul_f32_e32 v122, v94, v94
	v_pk_add_f32 v[124:125], v[124:125], v[124:125] op_sel_hi:[0,1]
	v_pk_fma_f32 v[132:133], v[94:95], v[94:95], v[122:123] op_sel_hi:[1,1,0]
	v_mul_f32_e32 v126, v92, v92
	v_mul_f32_e32 v132, v93, v93
	v_mul_f32_e32 v122, v90, v90
	v_mul_f32_e32 v124, v91, v91
	v_pk_add_f32 v[126:127], v[126:127], v[132:133]
	v_pk_add_f32 v[122:123], v[122:123], v[124:125]
	s_nop 0
	v_pk_add_f32 v[122:123], v[126:127], v[122:123]
	s_nop 0
	v_add_f32_e32 v89, v122, v123
	v_mov_b32_e32 v122, v89
	s_nop 1
	v_permlane16_swap_b32_e32 v122, v89
	v_cmp_lt_i32_e32 vcc, v210, v209
	s_waitcnt lgkmcnt(0)
	v_add_f32_e32 v89, v89, v122
	v_mov_b32_e32 v122, v89
	s_nop 1
	v_permlane32_swap_b32_e32 v122, v89
	s_nop 1
	v_add_f32_e32 v89, v89, v122
	v_fmamk_f32 v89, v89, 0x3c800000, v201
	v_rsq_f32_e32 v122, v89
; __device__ __forceinline__ unsigned cvt_pk_bf16(float lo, float hi) { unsigned r; asm volatile("v_cvt_pk_bf16_f32 %0, %1, %2" : "=v"(r) : "v"(lo), "v"(hi)); return r; }
; __device__ __forceinline__ void st16_wt(void* p, u32x4 v) { asm volatile("global_store_dwordx4 %0, %1, off sc1\n\ts_nop 1" :: "v"(p), "v"(v) : "memory"); }
;     __device__ __forceinline__ void operator()(const f32x4 (&acc)[2][2][4][2], const Unit& u, int wr, int wc, int fr, int fq) const {
;     ...
;                 for (int m = 0; m < 4; ++m) {
;                     const int row = row0 + ai * HALF + m * 16;
;                     const float rrow = __builtin_amdgcn_rsqf(rr8[ai][m] * (1.0f / 1024.0f) + 1e-6f);
;                     f32x4 v[2][2];
; #pragma unroll
;                     for (int bj = 0; bj < 2; ++bj)
; #pragma unroll
;                         for (int n = 0; n < 2; ++n) v[bj][n] = acc[ai][bj][m][n] * rrow + bb[bj][n];
;                     float rs = 1.f;
;                     if (type < 2) { float ss = 0.f;
; #pragma unroll
;                         for (int bj = 0; bj < 2; ++bj)
; #pragma unroll
;                             for (int n = 0; n < 2; ++n) { const f32x4 x = v[bj][n]; ss += (x[0] * x[0] + x[1] * x[1]) + (x[2] * x[2] + x[3] * x[3]); }
;                         ss += __shfl_xor(ss, 16); ss += __shfl_xor(ss, 32);
;                         rs = __builtin_amdgcn_rsqf(ss * (1.0f / 64.0f) + 1e-6f); }
;                     bf16_t* rowp = base + (size_t)row * 1024;
; #pragma unroll
;                     for (int bj = 0; bj < 2; ++bj) { const f32x4 v0 = v[bj][0] * rs * gg[bj][0], v1 = v[bj][1] * rs * gg[bj][1];
;                         u32x4 w; w.x = cvt_pk_bf16(v0[0], v0[1]); w.y = cvt_pk_bf16(v0[2], v0[3]); w.z = cvt_pk_bf16(v1[0], v1[1]); w.w = cvt_pk_bf16(v1[2], v1[3]);
;                         st16_wt(rowp + 32 * bj, w); } }
.LBB0_670:
	s_nop 0
	v_pk_mul_f32 v[110:111], v[110:111], v[122:123] op_sel_hi:[1,0]
	v_pk_mul_f32 v[120:121], v[120:121], v[122:123] op_sel_hi:[1,0]
	v_pk_mul_f32 v[106:107], v[106:107], v[122:123] op_sel_hi:[1,0]
	v_pk_mul_f32 v[108:109], v[108:109], v[122:123] op_sel_hi:[1,0]
	v_pk_mul_f32 v[94:95], v[94:95], v[122:123] op_sel_hi:[1,0]
	v_lshlrev_b64 v[124:125], 11, v[188:189]
	v_pk_mul_f32 v[110:111], v[74:75], v[110:111]
	v_pk_mul_f32 v[120:121], v[72:73], v[120:121]
	v_pk_mul_f32 v[126:127], v[86:87], v[106:107]
	v_pk_mul_f32 v[108:109], v[84:85], v[108:109]
	v_cvt_pk_bf16_f32 v106, v120, v121
	v_cvt_pk_bf16_f32 v107, v110, v111
	v_pk_mul_f32 v[104:105], v[104:105], v[122:123] op_sel_hi:[1,0]
	v_pk_mul_f32 v[94:95], v[98:99], v[94:95]
	v_pk_mul_f32 v[90:91], v[90:91], v[122:123] op_sel_hi:[1,0]
	v_fmamk_f32 v89, v206, 0x3a800000, v201
	v_lshl_add_u64 v[124:125], v[144:145], 0, v[124:125]
	v_cvt_pk_bf16_f32 v108, v108, v109
	v_cvt_pk_bf16_f32 v109, v126, v127
	v_pk_mul_f32 v[104:105], v[96:97], v[104:105]
	global_store_dwordx4 v[124:125], v[106:109], off sc1
	s_nop 1
	v_pk_mul_f32 v[92:93], v[92:93], v[122:123] op_sel_hi:[1,0]
	v_pk_mul_f32 v[106:107], v[114:115], v[90:91]
	v_cvt_pk_bf16_f32 v90, v104, v105
	v_cvt_pk_bf16_f32 v91, v94, v95
	v_rsq_f32_e32 v94, v89
	v_pk_mul_f32 v[92:93], v[112:113], v[92:93]
	v_lshl_add_u64 v[104:105], v[124:125], 0, 64
	v_cvt_pk_bf16_f32 v92, v92, v93
	v_cvt_pk_bf16_f32 v93, v106, v107
	v_pk_fma_f32 v[82:83], v[82:83], v[94:95], v[102:103] op_sel_hi:[1,0,1]
	global_store_dwordx4 v[104:105], v[90:93], off sc1
	s_nop 1
	v_pk_fma_f32 v[80:81], v[80:81], v[94:95], v[100:101] op_sel_hi:[1,0,1]
	v_pk_fma_f32 v[78:79], v[78:79], v[94:95], v[118:119] op_sel_hi:[1,0,1]
	v_pk_fma_f32 v[76:77], v[76:77], v[94:95], v[116:117] op_sel_hi:[1,0,1]
	v_pk_fma_f32 v[70:71], v[70:71], v[94:95], v[130:131] op_sel_hi:[1,0,1]
	v_pk_fma_f32 v[68:69], v[68:69], v[94:95], v[128:129] op_sel_hi:[1,0,1]
	v_pk_fma_f32 v[66:67], v[66:67], v[94:95], v[142:143] op_sel_hi:[1,0,1]
	s_and_b64 vcc, exec, s[38:39]
	v_pk_fma_f32 v[64:65], v[64:65], v[94:95], v[140:141] op_sel_hi:[1,0,1]
	s_cbranch_vccnz .LBB0_672
	v_pk_mul_f32 v[88:89], v[82:83], v[82:83]
	v_pk_mul_f32 v[90:91], v[80:81], v[80:81]
	v_cmp_lt_i32_e32 vcc, v211, v209
	v_pk_mov_b32 v[92:93], v[90:91], v[88:89] op_sel:[1,0]
	v_mov_b32_e32 v91, v89
	v_pk_add_f32 v[88:89], v[92:93], v[90:91]
	v_pk_mul_f32 v[90:91], v[78:79], v[78:79]
	v_pk_add_f32 v[88:89], v[88:89], v[88:89] op_sel_hi:[0,1]
	v_pk_mul_f32 v[92:93], v[76:77], v[76:77]
	v_mul_f32_e32 v88, v68, v68
	v_pk_mov_b32 v[94:95], v[92:93], v[90:91] op_sel:[1,0]
	v_mov_b32_e32 v93, v91
	v_pk_add_f32 v[90:91], v[94:95], v[92:93]
	v_pk_fma_f32 v[92:93], v[68:69], v[68:69], v[88:89] op_sel_hi:[1,1,0]
	v_mul_f32_e32 v88, v70, v70
	v_pk_add_f32 v[90:91], v[90:91], v[90:91] op_sel_hi:[0,1]
	v_pk_fma_f32 v[94:95], v[70:71], v[70:71], v[88:89] op_sel_hi:[1,1,0]
	v_mul_f32_e32 v92, v64, v64
	v_mul_f32_e32 v94, v65, v65
	v_mul_f32_e32 v88, v66, v66
	v_mul_f32_e32 v90, v67, v67
	v_pk_add_f32 v[92:93], v[92:93], v[94:95]
	v_pk_add_f32 v[88:89], v[88:89], v[90:91]
	s_nop 0
	v_pk_add_f32 v[88:89], v[92:93], v[88:89]
	s_nop 0
	v_add_f32_e32 v88, v88, v89
	v_mov_b32_e32 v89, v88
	s_nop 1
	v_permlane16_swap_b32_e32 v89, v88
	v_cmp_lt_i32_e32 vcc, v210, v209
	s_waitcnt lgkmcnt(0)
	v_add_f32_e32 v88, v88, v89
	v_mov_b32_e32 v89, v88
	s_nop 1
	v_permlane32_swap_b32_e32 v89, v88
	s_nop 1
	v_add_f32_e32 v88, v88, v89
	v_fmamk_f32 v88, v88, 0x3c800000, v201
	v_rsq_f32_e32 v88, v88
.LBB0_672:
	s_nop 0
	v_pk_mul_f32 v[82:83], v[82:83], v[88:89] op_sel_hi:[1,0]
	v_pk_mul_f32 v[80:81], v[80:81], v[88:89] op_sel_hi:[1,0]
	v_pk_mul_f32 v[78:79], v[78:79], v[88:89] op_sel_hi:[1,0]
	v_pk_mul_f32 v[76:77], v[76:77], v[88:89] op_sel_hi:[1,0]
	v_lshlrev_b64 v[90:91], 11, v[186:187]
	v_pk_mul_f32 v[82:83], v[74:75], v[82:83]
	v_pk_mul_f32 v[80:81], v[72:73], v[80:81]
	v_pk_mul_f32 v[92:93], v[86:87], v[78:79]
	v_pk_mul_f32 v[78:79], v[84:85], v[76:77]
	v_cvt_pk_bf16_f32 v76, v80, v81
	v_cvt_pk_bf16_f32 v77, v82, v83
	v_pk_mul_f32 v[66:67], v[66:67], v[88:89] op_sel_hi:[1,0]
	v_pk_mul_f32 v[64:65], v[64:65], v[88:89] op_sel_hi:[1,0]
	v_lshl_add_u64 v[90:91], v[144:145], 0, v[90:91]
	v_cvt_pk_bf16_f32 v78, v78, v79
	v_cvt_pk_bf16_f32 v79, v92, v93
	v_pk_mul_f32 v[70:71], v[70:71], v[88:89] op_sel_hi:[1,0]
	global_store_dwordx4 v[90:91], v[76:79], off sc1
	s_nop 1
	v_pk_mul_f32 v[68:69], v[68:69], v[88:89] op_sel_hi:[1,0]
	v_pk_mul_f32 v[76:77], v[114:115], v[66:67]
	v_pk_mul_f32 v[66:67], v[112:113], v[64:65]
	v_pk_mul_f32 v[70:71], v[98:99], v[70:71]
	v_pk_mul_f32 v[68:69], v[96:97], v[68:69]
	s_and_b64 vcc, exec, s[38:39]
	v_cvt_pk_bf16_f32 v64, v68, v69
	v_cvt_pk_bf16_f32 v65, v70, v71
	v_cvt_pk_bf16_f32 v66, v66, v67
	v_fmamk_f32 v67, v205, 0x3a800000, v201
	v_rsq_f32_e32 v68, v67
	v_cvt_pk_bf16_f32 v67, v76, v77
	v_lshl_add_u64 v[70:71], v[90:91], 0, 64
	global_store_dwordx4 v[70:71], v[64:67], off sc1
	s_nop 1
	v_pk_fma_f32 v[62:63], v[62:63], v[68:69], v[102:103] op_sel_hi:[1,0,1]
	v_pk_fma_f32 v[66:67], v[60:61], v[68:69], v[100:101] op_sel_hi:[1,0,1]
	v_pk_fma_f32 v[60:61], v[58:59], v[68:69], v[118:119] op_sel_hi:[1,0,1]
	v_pk_fma_f32 v[64:65], v[56:57], v[68:69], v[116:117] op_sel_hi:[1,0,1]
	v_pk_fma_f32 v[54:55], v[54:55], v[68:69], v[130:131] op_sel_hi:[1,0,1]
	v_pk_fma_f32 v[58:59], v[52:53], v[68:69], v[128:129] op_sel_hi:[1,0,1]
	v_pk_fma_f32 v[52:53], v[50:51], v[68:69], v[142:143] op_sel_hi:[1,0,1]
	v_pk_fma_f32 v[56:57], v[48:49], v[68:69], v[140:141] op_sel_hi:[1,0,1]
	v_mov_b32_e32 v50, 1.0
	v_mov_b32_e32 v68, 1.0
	s_cbranch_vccnz .LBB0_674
	v_pk_mul_f32 v[48:49], v[62:63], v[62:63]
	v_pk_mul_f32 v[68:69], v[66:67], v[66:67]
	v_cmp_lt_i32_e32 vcc, v211, v209
	v_pk_mov_b32 v[70:71], v[68:69], v[48:49] op_sel:[1,0]
	v_mov_b32_e32 v69, v49
	v_pk_add_f32 v[48:49], v[70:71], v[68:69]
	v_pk_mul_f32 v[68:69], v[60:61], v[60:61]
	v_pk_add_f32 v[48:49], v[48:49], v[48:49] op_sel_hi:[0,1]
	v_pk_mul_f32 v[70:71], v[64:65], v[64:65]
	v_mul_f32_e32 v48, v58, v58
	v_pk_mov_b32 v[76:77], v[70:71], v[68:69] op_sel:[1,0]
	v_mov_b32_e32 v71, v69
	v_pk_add_f32 v[68:69], v[76:77], v[70:71]
	v_pk_fma_f32 v[70:71], v[58:59], v[58:59], v[48:49] op_sel_hi:[1,1,0]
	v_mul_f32_e32 v48, v54, v54
	v_pk_add_f32 v[68:69], v[68:69], v[68:69] op_sel_hi:[0,1]
	v_pk_fma_f32 v[76:77], v[54:55], v[54:55], v[48:49] op_sel_hi:[1,1,0]
	v_mul_f32_e32 v70, v56, v56
	v_mul_f32_e32 v76, v57, v57
	v_mul_f32_e32 v48, v52, v52
	v_mul_f32_e32 v68, v53, v53
	v_pk_add_f32 v[70:71], v[70:71], v[76:77]
	v_pk_add_f32 v[48:49], v[48:49], v[68:69]
	s_nop 0
	v_pk_add_f32 v[48:49], v[70:71], v[48:49]
	s_nop 0
	v_add_f32_e32 v48, v48, v49
	v_mov_b32_e32 v49, v48
	s_nop 1
	v_permlane16_swap_b32_e32 v49, v48
	v_cmp_lt_i32_e32 vcc, v210, v209
	s_waitcnt lgkmcnt(0)
	v_add_f32_e32 v48, v48, v49
	v_mov_b32_e32 v49, v48
	s_nop 1
	v_permlane32_swap_b32_e32 v49, v48
	s_nop 1
	v_add_f32_e32 v48, v48, v49
	v_fmamk_f32 v48, v48, 0x3c800000, v201
	v_rsq_f32_e32 v68, v48
; __device__ __forceinline__ unsigned cvt_pk_bf16(float lo, float hi) { unsigned r; asm volatile("v_cvt_pk_bf16_f32 %0, %1, %2" : "=v"(r) : "v"(lo), "v"(hi)); return r; }
; __device__ __forceinline__ void st16_wt(void* p, u32x4 v) { asm volatile("global_store_dwordx4 %0, %1, off sc1\n\ts_nop 1" :: "v"(p), "v"(v) : "memory"); }
;     __device__ __forceinline__ void operator()(const f32x4 (&acc)[2][2][4][2], const Unit& u, int wr, int wc, int fr, int fq) const {
;     ...
;                 for (int m = 0; m < 4; ++m) {
;                     const int row = row0 + ai * HALF + m * 16;
;                     const float rrow = __builtin_amdgcn_rsqf(rr8[ai][m] * (1.0f / 1024.0f) + 1e-6f);
;                     f32x4 v[2][2];
; #pragma unroll
;                     for (int bj = 0; bj < 2; ++bj)
; #pragma unroll
;                         for (int n = 0; n < 2; ++n) v[bj][n] = acc[ai][bj][m][n] * rrow + bb[bj][n];
;                     float rs = 1.f;
;                     if (type < 2) { float ss = 0.f;
; #pragma unroll
;                         for (int bj = 0; bj < 2; ++bj)
; #pragma unroll
;                             for (int n = 0; n < 2; ++n) { const f32x4 x = v[bj][n]; ss += (x[0] * x[0] + x[1] * x[1]) + (x[2] * x[2] + x[3] * x[3]); }
;                         ss += __shfl_xor(ss, 16); ss += __shfl_xor(ss, 32);
;                         rs = __builtin_amdgcn_rsqf(ss * (1.0f / 64.0f) + 1e-6f); }
;                     bf16_t* rowp = base + (size_t)row * 1024;
; #pragma unroll
;                     for (int bj = 0; bj < 2; ++bj) { const f32x4 v0 = v[bj][0] * rs * gg[bj][0], v1 = v[bj][1] * rs * gg[bj][1];
;                         u32x4 w; w.x = cvt_pk_bf16(v0[0], v0[1]); w.y = cvt_pk_bf16(v0[2], v0[3]); w.z = cvt_pk_bf16(v1[0], v1[1]); w.w = cvt_pk_bf16(v1[2], v1[3]);
;                         st16_wt(rowp + 32 * bj, w); } }
.LBB0_674:
	v_lshlrev_b64 v[48:49], 11, v[184:185]
	v_pk_mul_f32 v[62:63], v[62:63], v[68:69] op_sel_hi:[1,0]
	v_pk_mul_f32 v[66:67], v[66:67], v[68:69] op_sel_hi:[1,0]
	v_pk_mul_f32 v[60:61], v[60:61], v[68:69] op_sel_hi:[1,0]
	v_pk_mul_f32 v[54:55], v[54:55], v[68:69] op_sel_hi:[1,0]
	v_pk_mul_f32 v[56:57], v[56:57], v[68:69] op_sel_hi:[1,0]
	v_lshl_add_u64 v[48:49], v[144:145], 0, v[48:49]
	s_mov_b64 s[14:15], 0x40000
	v_pk_mul_f32 v[62:63], v[74:75], v[62:63]
	v_pk_mul_f32 v[66:67], v[72:73], v[66:67]
	v_pk_mul_f32 v[64:65], v[64:65], v[68:69] op_sel_hi:[1,0]
	v_pk_mul_f32 v[76:77], v[86:87], v[60:61]
	v_cvt_pk_bf16_f32 v60, v66, v67
	v_cvt_pk_bf16_f32 v61, v62, v63
	v_pk_mul_f32 v[58:59], v[58:59], v[68:69] op_sel_hi:[1,0]
	v_pk_mul_f32 v[54:55], v[98:99], v[54:55]
	v_pk_mul_f32 v[52:53], v[52:53], v[68:69] op_sel_hi:[1,0]
	v_pk_mul_f32 v[56:57], v[112:113], v[56:57]
	v_fmamk_f32 v51, v204, 0x3a800000, v201
	v_lshl_add_u64 v[70:71], v[48:49], 0, s[14:15]
	v_pk_mul_f32 v[64:65], v[84:85], v[64:65]
	v_pk_mul_f32 v[58:59], v[96:97], v[58:59]
	v_cvt_pk_bf16_f32 v62, v64, v65
	v_cvt_pk_bf16_f32 v63, v76, v77
	s_mov_b64 s[14:15], 0x40040
	global_store_dwordx4 v[70:71], v[60:63], off sc1
	s_nop 1
	v_pk_mul_f32 v[60:61], v[114:115], v[52:53]
	v_cvt_pk_bf16_f32 v52, v58, v59
	v_cvt_pk_bf16_f32 v53, v54, v55
	v_cvt_pk_bf16_f32 v54, v56, v57
	v_rsq_f32_e32 v56, v51
	v_cvt_pk_bf16_f32 v55, v60, v61
	v_lshl_add_u64 v[58:59], v[48:49], 0, s[14:15]
	global_store_dwordx4 v[58:59], v[52:55], off sc1
	s_nop 1
	v_pk_fma_f32 v[46:47], v[46:47], v[56:57], v[102:103] op_sel_hi:[1,0,1]
	v_pk_fma_f32 v[44:45], v[44:45], v[56:57], v[100:101] op_sel_hi:[1,0,1]
	v_pk_fma_f32 v[42:43], v[42:43], v[56:57], v[118:119] op_sel_hi:[1,0,1]
	v_pk_fma_f32 v[40:41], v[40:41], v[56:57], v[116:117] op_sel_hi:[1,0,1]
	v_pk_fma_f32 v[38:39], v[38:39], v[56:57], v[130:131] op_sel_hi:[1,0,1]
	v_pk_fma_f32 v[36:37], v[36:37], v[56:57], v[128:129] op_sel_hi:[1,0,1]
	v_pk_fma_f32 v[34:35], v[34:35], v[56:57], v[142:143] op_sel_hi:[1,0,1]
	s_and_b64 vcc, exec, s[38:39]
	v_pk_fma_f32 v[32:33], v[32:33], v[56:57], v[140:141] op_sel_hi:[1,0,1]
	s_cbranch_vccnz .LBB0_676
	v_pk_mul_f32 v[50:51], v[46:47], v[46:47]
	v_pk_mul_f32 v[52:53], v[44:45], v[44:45]
	v_cmp_lt_i32_e32 vcc, v211, v209
	v_pk_mov_b32 v[54:55], v[52:53], v[50:51] op_sel:[1,0]
	v_mov_b32_e32 v53, v51
	v_pk_add_f32 v[50:51], v[54:55], v[52:53]
	v_pk_mul_f32 v[52:53], v[42:43], v[42:43]
	v_pk_add_f32 v[50:51], v[50:51], v[50:51] op_sel_hi:[0,1]
	v_pk_mul_f32 v[54:55], v[40:41], v[40:41]
	v_mul_f32_e32 v50, v36, v36
	v_pk_mov_b32 v[56:57], v[54:55], v[52:53] op_sel:[1,0]
	v_mov_b32_e32 v55, v53
	v_pk_add_f32 v[52:53], v[56:57], v[54:55]
	v_pk_fma_f32 v[54:55], v[36:37], v[36:37], v[50:51] op_sel_hi:[1,1,0]
	v_mul_f32_e32 v50, v38, v38
	v_pk_add_f32 v[52:53], v[52:53], v[52:53] op_sel_hi:[0,1]
	v_pk_fma_f32 v[56:57], v[38:39], v[38:39], v[50:51] op_sel_hi:[1,1,0]
	v_mul_f32_e32 v54, v32, v32
	v_mul_f32_e32 v56, v33, v33
	v_mul_f32_e32 v50, v34, v34
	v_mul_f32_e32 v52, v35, v35
	v_pk_add_f32 v[54:55], v[54:55], v[56:57]
	v_pk_add_f32 v[50:51], v[50:51], v[52:53]
	s_nop 0
	v_pk_add_f32 v[50:51], v[54:55], v[50:51]
	s_nop 0
	v_add_f32_e32 v50, v50, v51
	v_mov_b32_e32 v51, v50
	s_nop 1
	v_permlane16_swap_b32_e32 v51, v50
	v_cmp_lt_i32_e32 vcc, v210, v209
	s_waitcnt lgkmcnt(0)
	v_add_f32_e32 v50, v50, v51
	v_mov_b32_e32 v51, v50
	s_nop 1
	v_permlane32_swap_b32_e32 v51, v50
	s_nop 1
	v_add_f32_e32 v50, v50, v51
	v_fmamk_f32 v50, v50, 0x3c800000, v201
	v_rsq_f32_e32 v50, v50
; __device__ __forceinline__ unsigned cvt_pk_bf16(float lo, float hi) { unsigned r; asm volatile("v_cvt_pk_bf16_f32 %0, %1, %2" : "=v"(r) : "v"(lo), "v"(hi)); return r; }
; __device__ __forceinline__ void st16_wt(void* p, u32x4 v) { asm volatile("global_store_dwordx4 %0, %1, off sc1\n\ts_nop 1" :: "v"(p), "v"(v) : "memory"); }
;     __device__ __forceinline__ void operator()(const f32x4 (&acc)[2][2][4][2], const Unit& u, int wr, int wc, int fr, int fq) const {
;     ...
;                 for (int m = 0; m < 4; ++m) {
;                     const int row = row0 + ai * HALF + m * 16;
;                     const float rrow = __builtin_amdgcn_rsqf(rr8[ai][m] * (1.0f / 1024.0f) + 1e-6f);
;                     f32x4 v[2][2];
; #pragma unroll
;                     for (int bj = 0; bj < 2; ++bj)
; #pragma unroll
;                         for (int n = 0; n < 2; ++n) v[bj][n] = acc[ai][bj][m][n] * rrow + bb[bj][n];
;                     float rs = 1.f;
;                     if (type < 2) { float ss = 0.f;
; #pragma unroll
;                         for (int bj = 0; bj < 2; ++bj)
; #pragma unroll
;                             for (int n = 0; n < 2; ++n) { const f32x4 x = v[bj][n]; ss += (x[0] * x[0] + x[1] * x[1]) + (x[2] * x[2] + x[3] * x[3]); }
;                         ss += __shfl_xor(ss, 16); ss += __shfl_xor(ss, 32);
;                         rs = __builtin_amdgcn_rsqf(ss * (1.0f / 64.0f) + 1e-6f); }
;                     bf16_t* rowp = base + (size_t)row * 1024;
; #pragma unroll
;                     for (int bj = 0; bj < 2; ++bj) { const f32x4 v0 = v[bj][0] * rs * gg[bj][0], v1 = v[bj][1] * rs * gg[bj][1];
;                         u32x4 w; w.x = cvt_pk_bf16(v0[0], v0[1]); w.y = cvt_pk_bf16(v0[2], v0[3]); w.z = cvt_pk_bf16(v1[0], v1[1]); w.w = cvt_pk_bf16(v1[2], v1[3]);
;                         st16_wt(rowp + 32 * bj, w); } }
.LBB0_676:
	s_nop 0
	v_pk_mul_f32 v[46:47], v[46:47], v[50:51] op_sel_hi:[1,0]
	v_pk_mul_f32 v[44:45], v[44:45], v[50:51] op_sel_hi:[1,0]
	v_pk_mul_f32 v[42:43], v[42:43], v[50:51] op_sel_hi:[1,0]
	v_pk_mul_f32 v[40:41], v[40:41], v[50:51] op_sel_hi:[1,0]
	s_mov_b64 s[14:15], 0x48000
	v_pk_mul_f32 v[46:47], v[74:75], v[46:47]
	v_pk_mul_f32 v[44:45], v[72:73], v[44:45]
	v_pk_mul_f32 v[54:55], v[86:87], v[42:43]
	v_pk_mul_f32 v[42:43], v[84:85], v[40:41]
	v_cvt_pk_bf16_f32 v40, v44, v45
	v_cvt_pk_bf16_f32 v41, v46, v47
	v_pk_mul_f32 v[34:35], v[34:35], v[50:51] op_sel_hi:[1,0]
	v_pk_mul_f32 v[32:33], v[32:33], v[50:51] op_sel_hi:[1,0]
	v_lshl_add_u64 v[52:53], v[48:49], 0, s[14:15]
	v_cvt_pk_bf16_f32 v42, v42, v43
	v_cvt_pk_bf16_f32 v43, v54, v55
	v_pk_mul_f32 v[38:39], v[38:39], v[50:51] op_sel_hi:[1,0]
	global_store_dwordx4 v[52:53], v[40:43], off sc1
	s_nop 1
	v_pk_mul_f32 v[36:37], v[36:37], v[50:51] op_sel_hi:[1,0]
	v_pk_mul_f32 v[40:41], v[114:115], v[34:35]
	v_pk_mul_f32 v[34:35], v[112:113], v[32:33]
	v_pk_mul_f32 v[38:39], v[98:99], v[38:39]
	v_pk_mul_f32 v[36:37], v[96:97], v[36:37]
	s_mov_b64 s[14:15], 0x48040
	v_cvt_pk_bf16_f32 v32, v36, v37
	v_cvt_pk_bf16_f32 v33, v38, v39
	v_cvt_pk_bf16_f32 v34, v34, v35
	v_fmamk_f32 v35, v203, 0x3a800000, v201
	v_rsq_f32_e32 v36, v35
	v_cvt_pk_bf16_f32 v35, v40, v41
	v_lshl_add_u64 v[38:39], v[48:49], 0, s[14:15]
	global_store_dwordx4 v[38:39], v[32:35], off sc1
	s_nop 1
	v_pk_fma_f32 v[30:31], v[30:31], v[36:37], v[102:103] op_sel_hi:[1,0,1]
	v_pk_fma_f32 v[34:35], v[28:29], v[36:37], v[100:101] op_sel_hi:[1,0,1]
	v_pk_fma_f32 v[28:29], v[26:27], v[36:37], v[118:119] op_sel_hi:[1,0,1]
	v_pk_fma_f32 v[32:33], v[24:25], v[36:37], v[116:117] op_sel_hi:[1,0,1]
	v_pk_fma_f32 v[22:23], v[22:23], v[36:37], v[130:131] op_sel_hi:[1,0,1]
	v_pk_fma_f32 v[26:27], v[20:21], v[36:37], v[128:129] op_sel_hi:[1,0,1]
	v_pk_fma_f32 v[20:21], v[18:19], v[36:37], v[142:143] op_sel_hi:[1,0,1]
	v_pk_fma_f32 v[24:25], v[16:17], v[36:37], v[140:141] op_sel_hi:[1,0,1]
	v_mov_b32_e32 v18, 1.0
	s_and_b64 vcc, exec, s[38:39]
	v_mov_b32_e32 v36, 1.0
	s_cbranch_vccnz .LBB0_678
	v_pk_mul_f32 v[16:17], v[30:31], v[30:31]
	v_pk_mul_f32 v[36:37], v[34:35], v[34:35]
	v_cmp_lt_i32_e32 vcc, v211, v209
	v_pk_mov_b32 v[38:39], v[36:37], v[16:17] op_sel:[1,0]
	v_mov_b32_e32 v37, v17
	v_pk_add_f32 v[16:17], v[38:39], v[36:37]
	v_pk_mul_f32 v[36:37], v[28:29], v[28:29]
	v_pk_add_f32 v[16:17], v[16:17], v[16:17] op_sel_hi:[0,1]
	v_pk_mul_f32 v[38:39], v[32:33], v[32:33]
	v_mul_f32_e32 v16, v26, v26
	v_pk_mov_b32 v[40:41], v[38:39], v[36:37] op_sel:[1,0]
	v_mov_b32_e32 v39, v37
	v_pk_add_f32 v[36:37], v[40:41], v[38:39]
	v_pk_fma_f32 v[38:39], v[26:27], v[26:27], v[16:17] op_sel_hi:[1,1,0]
	v_mul_f32_e32 v16, v22, v22
	v_pk_add_f32 v[36:37], v[36:37], v[36:37] op_sel_hi:[0,1]
	v_pk_fma_f32 v[40:41], v[22:23], v[22:23], v[16:17] op_sel_hi:[1,1,0]
	v_mul_f32_e32 v38, v24, v24
	v_mul_f32_e32 v40, v25, v25
	v_mul_f32_e32 v16, v20, v20
	v_mul_f32_e32 v36, v21, v21
	v_pk_add_f32 v[38:39], v[38:39], v[40:41]
	v_pk_add_f32 v[16:17], v[16:17], v[36:37]
	s_nop 0
	v_pk_add_f32 v[16:17], v[38:39], v[16:17]
	s_nop 0
	v_add_f32_e32 v16, v16, v17
	v_mov_b32_e32 v17, v16
	s_nop 1
	v_permlane16_swap_b32_e32 v17, v16
	v_cmp_lt_i32_e32 vcc, v210, v209
	s_waitcnt lgkmcnt(0)
	v_add_f32_e32 v16, v16, v17
	v_mov_b32_e32 v17, v16
	s_nop 1
	v_permlane32_swap_b32_e32 v17, v16
	s_nop 1
	v_add_f32_e32 v16, v16, v17
	v_fmamk_f32 v16, v16, 0x3c800000, v201
	v_rsq_f32_e32 v36, v16
.LBB0_678:
	v_lshlrev_b64 v[16:17], 11, v[184:185]
	v_pk_mul_f32 v[30:31], v[30:31], v[36:37] op_sel_hi:[1,0]
	v_pk_mul_f32 v[34:35], v[34:35], v[36:37] op_sel_hi:[1,0]
	v_pk_mul_f32 v[28:29], v[28:29], v[36:37] op_sel_hi:[1,0]
	v_pk_mul_f32 v[22:23], v[22:23], v[36:37] op_sel_hi:[1,0]
	v_pk_mul_f32 v[24:25], v[24:25], v[36:37] op_sel_hi:[1,0]
	v_lshl_add_u64 v[16:17], v[144:145], 0, v[16:17]
	s_mov_b64 s[14:15], 0x50000
	v_pk_mul_f32 v[30:31], v[74:75], v[30:31]
	v_pk_mul_f32 v[34:35], v[72:73], v[34:35]
	v_pk_mul_f32 v[32:33], v[32:33], v[36:37] op_sel_hi:[1,0]
	v_pk_mul_f32 v[40:41], v[86:87], v[28:29]
	v_cvt_pk_bf16_f32 v28, v34, v35
	v_cvt_pk_bf16_f32 v29, v30, v31
	v_pk_mul_f32 v[26:27], v[26:27], v[36:37] op_sel_hi:[1,0]
	v_pk_mul_f32 v[22:23], v[98:99], v[22:23]
	v_pk_mul_f32 v[20:21], v[20:21], v[36:37] op_sel_hi:[1,0]
	v_pk_mul_f32 v[24:25], v[112:113], v[24:25]
	v_fmamk_f32 v19, v202, 0x3a800000, v201
	v_lshl_add_u64 v[38:39], v[16:17], 0, s[14:15]
	v_pk_mul_f32 v[32:33], v[84:85], v[32:33]
	v_pk_mul_f32 v[26:27], v[96:97], v[26:27]
	v_cvt_pk_bf16_f32 v30, v32, v33
	v_cvt_pk_bf16_f32 v31, v40, v41
	s_mov_b64 s[14:15], 0x50040
	global_store_dwordx4 v[38:39], v[28:31], off sc1
	s_nop 1
	v_pk_mul_f32 v[28:29], v[114:115], v[20:21]
	v_cvt_pk_bf16_f32 v20, v26, v27
	v_cvt_pk_bf16_f32 v21, v22, v23
	v_cvt_pk_bf16_f32 v22, v24, v25
	v_rsq_f32_e32 v24, v19
	v_cvt_pk_bf16_f32 v23, v28, v29
	v_lshl_add_u64 v[26:27], v[16:17], 0, s[14:15]
	global_store_dwordx4 v[26:27], v[20:23], off sc1
	s_nop 1
	v_pk_fma_f32 v[14:15], v[14:15], v[24:25], v[102:103] op_sel_hi:[1,0,1]
	v_pk_fma_f32 v[12:13], v[12:13], v[24:25], v[100:101] op_sel_hi:[1,0,1]
	v_pk_fma_f32 v[10:11], v[10:11], v[24:25], v[118:119] op_sel_hi:[1,0,1]
	v_pk_fma_f32 v[8:9], v[8:9], v[24:25], v[116:117] op_sel_hi:[1,0,1]
	v_pk_fma_f32 v[6:7], v[6:7], v[24:25], v[130:131] op_sel_hi:[1,0,1]
	v_pk_fma_f32 v[4:5], v[4:5], v[24:25], v[128:129] op_sel_hi:[1,0,1]
	v_pk_fma_f32 v[2:3], v[2:3], v[24:25], v[142:143] op_sel_hi:[1,0,1]
	s_and_b64 vcc, exec, s[38:39]
	v_pk_fma_f32 v[0:1], v[0:1], v[24:25], v[140:141] op_sel_hi:[1,0,1]
	s_cbranch_vccnz .LBB0_680
	v_pk_mul_f32 v[18:19], v[14:15], v[14:15]
	v_pk_mul_f32 v[20:21], v[12:13], v[12:13]
	v_cmp_lt_i32_e32 vcc, v211, v209
	v_pk_mov_b32 v[22:23], v[20:21], v[18:19] op_sel:[1,0]
	v_mov_b32_e32 v21, v19
	v_pk_add_f32 v[18:19], v[22:23], v[20:21]
	v_pk_mul_f32 v[20:21], v[10:11], v[10:11]
	v_pk_add_f32 v[18:19], v[18:19], v[18:19] op_sel_hi:[0,1]
	v_pk_mul_f32 v[22:23], v[8:9], v[8:9]
	v_mul_f32_e32 v18, v4, v4
	v_pk_mov_b32 v[24:25], v[22:23], v[20:21] op_sel:[1,0]
	v_mov_b32_e32 v23, v21
	v_pk_add_f32 v[20:21], v[24:25], v[22:23]
	v_pk_fma_f32 v[22:23], v[4:5], v[4:5], v[18:19] op_sel_hi:[1,1,0]
	v_mul_f32_e32 v18, v6, v6
	v_pk_add_f32 v[20:21], v[20:21], v[20:21] op_sel_hi:[0,1]
	v_pk_fma_f32 v[24:25], v[6:7], v[6:7], v[18:19] op_sel_hi:[1,1,0]
	v_mul_f32_e32 v22, v0, v0
	v_mul_f32_e32 v24, v1, v1
	v_mul_f32_e32 v18, v2, v2
	v_mul_f32_e32 v20, v3, v3
	v_pk_add_f32 v[22:23], v[22:23], v[24:25]
	v_pk_add_f32 v[18:19], v[18:19], v[20:21]
	s_nop 0
	v_pk_add_f32 v[18:19], v[22:23], v[18:19]
	s_nop 0
	v_add_f32_e32 v18, v18, v19
	v_mov_b32_e32 v19, v18
	s_nop 1
	v_permlane16_swap_b32_e32 v19, v18
	v_cmp_lt_i32_e32 vcc, v210, v209
	s_waitcnt lgkmcnt(0)
	v_add_f32_e32 v18, v18, v19
	v_mov_b32_e32 v19, v18
	s_nop 1
	v_permlane32_swap_b32_e32 v19, v18
	s_nop 1
	v_add_f32_e32 v18, v18, v19
	v_fmamk_f32 v18, v18, 0x3c800000, v201
	v_rsq_f32_e32 v18, v18
